# XCD-hierarchical grid barrier (one L2 writeback per XCC by last arriver, per-WG acquire only), trimmed redundant fence halves, tighter polling
# speedup vs baseline: 1.1650x; 1.1650x over previous
; __global__ void __launch_bounds__(256, 2) mega(Params p, int ph0, int ph1) {
;   __shared__ __attribute__((aligned(16))) unsigned char smem[SMEM_TOTAL];
;   const int wave_in_block = __builtin_amdgcn_readfirstlane((int)(__builtin_amdgcn_workitem_id_x() >> 6));
;   for (int ph = ph0; ph < ph1; ++ph) {
;     int wv_ = wave_in_block;
;     asm volatile("" : "+s"(wv_));
;     int TIDX = wv_ * 64 + (int)__lane_id();
;     asm volatile("" : "+v"(TIDX));
;     int BIDX = __builtin_amdgcn_workgroup_id_x(), GDIM = (int)gridDim.x;
;     asm volatile("" : "+s"(BIDX), "+s"(GDIM));
_Z4mega6Paramsii:
	v_and_b32_e32 v1, 0x3ff, v0
	s_mov_b32 s100, 0
	v_writelane_b32 v255, s2, 0
	v_writelane_b32 v255, s0, 1
	s_nop 1
	v_writelane_b32 v255, s1, 2
	s_load_dwordx2 s[0:1], s[0:1], 0x108
	s_waitcnt lgkmcnt(0)
	v_writelane_b32 v255, s0, 3
	s_nop 1
	v_writelane_b32 v255, s1, 4
	s_cmp_ge_i32 s0, s1
	v_readfirstlane_b32 s0, v1
	s_cbranch_scc0 .LBB0_1
	s_getpc_b64 s[98:99]

; DEVI void grid_barrier(const int TIDX, const int BIDX, const int GDIM, unsigned* bar, unsigned k) {
;   __syncthreads();
;   if (TIDX == 0) {
;     __threadfence();
;     const unsigned g = (unsigned)BIDX & 7u, gs = (unsigned)GDIM >> 3;
;     const unsigned old = __hip_atomic_fetch_add(bar + 32 * (1 + g), 1u, __ATOMIC_RELAXED, __HIP_MEMORY_SCOPE_AGENT);
;     if (old + 1u == gs * k) {
;       __threadfence();
;       __hip_atomic_fetch_add(bar, 1u, __ATOMIC_RELAXED, __HIP_MEMORY_SCOPE_AGENT);
;     }
;     unsigned spins = 0;
;     while (__hip_atomic_load(bar, __ATOMIC_RELAXED, __HIP_MEMORY_SCOPE_AGENT) < 8u * k) {
;       __builtin_amdgcn_s_sleep(1);
;       if (++spins > (1u << 27)) break;
;     }
;     __threadfence();
;   }
;   __syncthreads();
; }
.LBB0_787:
	v_readlane_b32 s0, v255, 3
	v_readlane_b32 s1, v255, 4
	s_cmp_lg_u32 s12, s0
	s_mov_b64 s[0:1], -1
	s_cbranch_scc0 .LBB0_811
	v_cmp_eq_u32_e32 vcc, 0, v130
	s_waitcnt vmcnt(0) lgkmcnt(0)
	s_barrier
	s_and_saveexec_b64 s[0:1], vcc
	s_cbranch_execz .LBB0_810
	s_add_u32 s2, s50, 0x22a9800
	s_addc_u32 s3, s51, 0
	s_getreg_b32 s4, hwreg(HW_REG_XCC_ID, 0, 4)
	s_lshl_b32 s4, s4, 6
	v_mov_b32_e32 v0, s4
	s_cmp_lg_u32 s100, 0
	s_cbranch_scc1 .Lxb_have
	global_load_dword v1, v0, s[2:3] sc1
	s_waitcnt vmcnt(0)
	v_readfirstlane_b32 s100, v1
.Lxb_have:
	v_readlane_b32 s6, v255, 3
	s_sub_i32 s9, s12, s6
	v_mov_b32_e32 v1, 1
	global_atomic_add v1, v0, v1, s[2:3] offset:16 sc0
	s_mul_i32 s5, s100, s9
	s_mov_b32 s10, 0x4000
	s_waitcnt vmcnt(0)
	v_readfirstlane_b32 s7, v1
	s_add_i32 s7, s7, 1
	s_cmp_eq_u32 s7, s5
	s_cbranch_scc0 .Lxb_follow
	buffer_wbl2 sc1
	s_waitcnt vmcnt(0)
	v_mov_b32_e32 v1, s100
	v_mov_b32_e32 v2, 0x400
	global_atomic_add v1, v2, v1, s[2:3] sc0
	s_mul_i32 s5, s84, s9
	v_mov_b32_e32 v2, 0x480
	s_waitcnt vmcnt(0)
	v_readfirstlane_b32 s7, v1
	s_add_i32 s7, s7, s100
	s_cmp_eq_u32 s7, s5
	s_cbranch_scc0 .Lxb_spin_top
	v_mov_b32_e32 v1, 1
	global_atomic_add v2, v1, s[2:3]
	s_branch .Lxb_lead_rel
.Lxb_spin_top:
	global_load_dword v1, v2, s[2:3] sc1
	s_waitcnt vmcnt(0)
	v_readfirstlane_b32 s7, v1
	s_cmp_ge_u32 s7, s9
	s_cbranch_scc1 .Lxb_lead_rel
	s_add_i32 s10, s10, -1
	s_cmp_eq_u32 s10, 0
	s_cbranch_scc1 .Lxb_lead_rel
	s_nop 7
	s_branch .Lxb_spin_top
.Lxb_lead_rel:
	buffer_inv sc1
	v_mov_b32_e32 v1, 1
	global_atomic_add v0, v1, s[2:3] offset:32
	s_waitcnt vmcnt(0)
	s_branch .LBB0_810
.Lxb_follow:
	global_load_dword v1, v0, s[2:3] offset:32 sc1
	s_waitcnt vmcnt(0)
	v_readfirstlane_b32 s7, v1
	s_cmp_ge_u32 s7, s9
	s_cbranch_scc1 .Lxb_facq
	s_add_i32 s10, s10, -1
	s_cmp_eq_u32 s10, 0
	s_cbranch_scc1 .Lxb_facq
	s_nop 7
	s_branch .Lxb_follow
.Lxb_facq:
	buffer_inv sc1
	s_waitcnt vmcnt(0)
	s_branch .LBB0_810

; DEVI void phase_prep(const int TIDX, const int BIDX, const int GDIM, KAP KA, unsigned char* WSB, float* OUTB, unsigned char* smem) {
;     ...
;   if (gtid < 32) ((int*)(WSB + O_CNT))[3072 + (gtid >> 1) * 32 + (gtid & 1) * 16] = 0;
; DEVI void grid_barrier(const int TIDX, const int BIDX, const int GDIM, unsigned* bar, unsigned k) {
;     ...
;     __threadfence();
;   }
;   __syncthreads();
.LBB0_808:
	v_lshlrev_b32_e32 v3, 4, v130
	v_lshlrev_b32_e32 v2, 4, v0
	v_and_b32_e32 v3, 16, v3
	s_movk_i32 s2, 0xffe0
	v_and_or_b32 v2, v2, s2, v3
	v_add_u32_e32 v2, 0xc00, v2
	v_ashrrev_i32_e32 v3, 31, v2
	s_waitcnt lgkmcnt(0)
	v_lshl_add_u64 v[2:3], v[2:3], 2, s[50:51]
	v_add_co_u32_e32 v2, vcc, 0x22a9000, v2
	s_nop 1
	v_addc_co_u32_e32 v3, vcc, 0, v3, vcc
	global_store_dword v[2:3], v129, off
	s_or_b64 exec, exec, s[0:1]
	s_and_saveexec_b64 s[0:1], s[4:5]
	s_cbranch_execnz .LBB0_699
	s_branch .LBB0_700
.LBB0_810:
	s_or_b64 exec, exec, s[0:1]
	s_mov_b64 s[0:1], 0
	s_barrier

; __global__ void __launch_bounds__(256, 2) mega(Params p, int ph0, int ph1) {
;     ...
;     if (ph + 1 < ph1) {
;       if (ph == ph0) cg::this_grid().sync();
.LBB0_812:
	v_cmp_eq_u32_e32 vcc, 0, v130
	s_and_saveexec_b64 s[4:5], vcc
	s_cbranch_execz .Lxb_posted
	s_add_u32 s2, s50, 0x22a9800
	s_addc_u32 s3, s51, 0
	s_getreg_b32 s6, hwreg(HW_REG_XCC_ID, 0, 4)
	s_lshl_b32 s6, s6, 6
	v_mov_b32_e32 v0, s6
	v_mov_b32_e32 v1, 1
	global_atomic_add v0, v1, s[2:3]
	s_waitcnt vmcnt(0)
.Lxb_posted:
	s_or_b64 exec, exec, s[4:5]
	s_waitcnt lgkmcnt(0)
	s_barrier
	s_mov_b64 s[0:1], exec
	v_readlane_b32 s2, v255, 8
	v_readlane_b32 s3, v255, 9
	s_and_b64 s[2:3], s[0:1], s[2:3]
	s_mov_b64 exec, s[2:3]
	s_cbranch_execnz .LBB0_813
	s_getpc_b64 s[98:99]

; __global__ void __launch_bounds__(256, 2) mega(Params p, int ph0, int ph1) {
;   __shared__ __attribute__((aligned(16))) unsigned char smem[SMEM_TOTAL];
	.amdhsa_kernel _Z4mega6Paramsii
		.amdhsa_group_segment_fixed_size 75776
		.amdhsa_private_segment_fixed_size 0
		.amdhsa_kernarg_size 528
		.amdhsa_user_sgpr_count 2
		.amdhsa_user_sgpr_dispatch_ptr 0
		.amdhsa_user_sgpr_queue_ptr 0
		.amdhsa_user_sgpr_kernarg_segment_ptr 1
		.amdhsa_user_sgpr_dispatch_id 0
		.amdhsa_user_sgpr_kernarg_preload_length 0
		.amdhsa_user_sgpr_kernarg_preload_offset 0
		.amdhsa_user_sgpr_private_segment_size 0
		.amdhsa_uses_dynamic_stack 0
		.amdhsa_enable_private_segment 0
		.amdhsa_system_sgpr_workgroup_id_x 1
		.amdhsa_system_sgpr_workgroup_id_y 0
		.amdhsa_system_sgpr_workgroup_id_z 0
		.amdhsa_system_sgpr_workgroup_info 0
		.amdhsa_system_vgpr_workitem_id 2
		.amdhsa_next_free_vgpr 256
		.amdhsa_next_free_sgpr 102
		.amdhsa_accum_offset 256
		.amdhsa_reserve_vcc 1
		.amdhsa_float_round_mode_32 0
		.amdhsa_float_round_mode_16_64 0
		.amdhsa_float_denorm_mode_32 3
		.amdhsa_float_denorm_mode_16_64 3
		.amdhsa_dx10_clamp 1
		.amdhsa_ieee_mode 1
		.amdhsa_fp16_overflow 0
		.amdhsa_tg_split 0
		.amdhsa_exception_fp_ieee_invalid_op 0
		.amdhsa_exception_fp_denorm_src 0
		.amdhsa_exception_fp_ieee_div_zero 0
		.amdhsa_exception_fp_ieee_overflow 0
		.amdhsa_exception_fp_ieee_underflow 0
		.amdhsa_exception_fp_ieee_inexact 0
		.amdhsa_exception_int_div_zero 0
	.end_amdhsa_kernel

; __global__ void __launch_bounds__(256, 2) mega(Params p, int ph0, int ph1) {
;   __shared__ __attribute__((aligned(16))) unsigned char smem[SMEM_TOTAL];
amdhsa.kernels:
  - .agpr_count:     0
    .args:
      - .offset:         0
        .size:           264
        .value_kind:     by_value
      - .offset:         264
        .size:           4
        .value_kind:     by_value
      - .offset:         268
        .size:           4
        .value_kind:     by_value
      - .offset:         272
        .size:           4
        .value_kind:     hidden_block_count_x
      - .offset:         276
        .size:           4
        .value_kind:     hidden_block_count_y
      - .offset:         280
        .size:           4
        .value_kind:     hidden_block_count_z
      - .offset:         284
        .size:           2
        .value_kind:     hidden_group_size_x
      - .offset:         286
        .size:           2
        .value_kind:     hidden_group_size_y
      - .offset:         288
        .size:           2
        .value_kind:     hidden_group_size_z
      - .offset:         290
        .size:           2
        .value_kind:     hidden_remainder_x
      - .offset:         292
        .size:           2
        .value_kind:     hidden_remainder_y
      - .offset:         294
        .size:           2
        .value_kind:     hidden_remainder_z
      - .offset:         312
        .size:           8
        .value_kind:     hidden_global_offset_x
      - .offset:         320
        .size:           8
        .value_kind:     hidden_global_offset_y
      - .offset:         328
        .size:           8
        .value_kind:     hidden_global_offset_z
      - .offset:         336
        .size:           2
        .value_kind:     hidden_grid_dims
      - .offset:         360
        .size:           8
        .value_kind:     hidden_multigrid_sync_arg
    .group_segment_fixed_size: 75776
    .kernarg_segment_align: 8
    .kernarg_segment_size: 528
    .language:       OpenCL C
    .language_version:
      - 2
      - 0
    .max_flat_workgroup_size: 256
    .name:           _Z4mega6Paramsii
    .private_segment_fixed_size: 0
    .sgpr_count:     108
    .sgpr_spill_count: 42
    .symbol:         _Z4mega6Paramsii.kd
    .uniform_work_group_size: 1
    .uses_dynamic_stack: false
    .vgpr_count:     256
    .vgpr_spill_count: 0
    .wavefront_size: 64
